# scans: LDS fragment reads issued before the LDS-DMA issue block of each interval; HGRN2 scan: dropped a redundant vmcnt(0) after the O store; RN rebalance 18/10
# speedup vs baseline: 1.0219x; 1.0042x over previous
.LBB0_455:
	s_add_u32 s2, s8, 0xd100000
	s_addc_u32 s3, s9, 0
	s_abs_i32 s19, s18
	v_cvt_f32_u32_e32 v0, s19
	s_add_i32 s20, s18, 0x7fff
	s_sub_i32 s21, 0xffff8001, s18
	s_xor_b32 s18, s20, s18
	v_rcp_iflag_f32_e32 v0, v0
	s_max_i32 s20, s20, s21
	s_sub_i32 s21, 0, s19
	s_ashr_i32 s18, s18, 31
	v_mul_f32_e32 v0, 0x4f7ffffe, v0
	v_cvt_u32_f32_e32 v0, v0
	v_lshlrev_b32_e32 v122, 5, v24
	v_readfirstlane_b32 s22, v0
	s_mul_i32 s21, s21, s22
	s_mul_hi_u32 s21, s22, s21
	s_add_i32 s22, s22, s21
	s_mul_hi_u32 s21, s20, s22
	s_mul_i32 s22, s21, s19
	s_sub_i32 s20, s20, s22
	s_add_i32 s23, s21, 1
	s_sub_i32 s22, s20, s19
	s_cmp_ge_u32 s20, s19
	s_cselect_b32 s21, s23, s21
	s_cselect_b32 s20, s22, s20
	s_add_i32 s22, s21, 1
	s_cmp_ge_u32 s20, s19
	s_cselect_b32 s19, s22, s21
	s_xor_b32 s19, s19, s18
	s_sub_i32 s19, s19, s18
	s_mul_i32 s18, s19, s50
	s_add_i32 s19, s18, s19
	s_min_i32 s24, s19, 0x8000
	s_mul_i32 s98, s50, 18
	s_add_i32 s99, s50, 0xfffffa00
	s_mul_i32 s99, s99, 10
	s_addk_i32 s99, 0x6c00
	s_cmpk_lt_i32 s50, 0x600
	s_cselect_b32 s18, s98, s99
	s_cselect_b32 s98, 18, 10
	s_add_i32 s24, s18, s98
	s_cmp_lt_i32 s18, s24
	s_cselect_b64 s[20:21], -1, 0
	s_cmp_ge_i32 s18, s24
	s_cbranch_scc1 .LBB0_458
	s_ashr_i32 s19, s18, 31
	s_lshl_b64 s[22:23], s[18:19], 12
	s_add_u32 s22, s6, s22
	s_addc_u32 s23, s7, s23
	global_load_dwordx4 v[100:103], v122, s[22:23] offset:16
	global_load_dwordx4 v[108:111], v122, s[22:23]
	global_load_dwordx4 v[96:99], v122, s[22:23] offset:2064
	global_load_dwordx4 v[104:107], v122, s[22:23] offset:2048
	s_lshl_b64 s[22:23], s[18:19], 11
	s_add_u32 s22, s2, s22
	s_addc_u32 s23, s3, s23
	global_load_dwordx4 v[116:119], v120, s[22:23]
	global_load_dwordx4 v[112:115], v120, s[22:23] offset:1024
	s_add_i32 s22, s18, 1
	s_cmp_ge_i32 s22, s24
	s_cbranch_scc0 .LBB0_459

.LBB0_674:
	s_add_u32 s2, s12, 0x54000000
	s_addc_u32 s3, s13, 0
	s_add_u32 s20, s14, 0xd100000
	s_addc_u32 s21, s15, 0
	s_abs_i32 s19, s18
	v_cvt_f32_u32_e32 v0, s19
	s_add_i32 s22, s18, 0x7fff
	s_sub_i32 s23, 0xffff8001, s18
	s_xor_b32 s18, s22, s18
	v_rcp_iflag_f32_e32 v0, v0
	s_max_i32 s22, s22, s23
	s_sub_i32 s23, 0, s19
	s_ashr_i32 s18, s18, 31
	v_mul_f32_e32 v0, 0x4f7ffffe, v0
	v_cvt_u32_f32_e32 v0, v0
	s_nop 0
	v_readfirstlane_b32 s24, v0
	s_mul_i32 s23, s23, s24
	s_mul_hi_u32 s23, s24, s23
	s_add_i32 s24, s24, s23
	s_mul_hi_u32 s23, s22, s24
	s_mul_i32 s24, s23, s19
	s_sub_i32 s22, s22, s24
	s_add_i32 s25, s23, 1
	s_sub_i32 s24, s22, s19
	s_cmp_ge_u32 s22, s19
	s_cselect_b32 s23, s25, s23
	s_cselect_b32 s22, s24, s22
	s_add_i32 s24, s23, 1
	s_cmp_ge_u32 s22, s19
	s_cselect_b32 s19, s24, s23
	s_xor_b32 s19, s19, s18
	s_sub_i32 s19, s19, s18
	s_mul_i32 s18, s19, s48
	s_add_i32 s19, s18, s19
	s_min_i32 s26, s19, 0x8000
	s_mul_i32 s98, s48, 18
	s_add_i32 s99, s48, 0xfffffa00
	s_mul_i32 s99, s99, 10
	s_addk_i32 s99, 0x6c00
	s_cmpk_lt_i32 s48, 0x600
	s_cselect_b32 s18, s98, s99
	s_cselect_b32 s98, 18, 10
	s_add_i32 s26, s18, s98
	s_cmp_lt_i32 s18, s26
	s_cselect_b64 s[22:23], -1, 0
	s_cmp_ge_i32 s18, s26
	s_cbranch_scc1 .LBB0_676
	s_ashr_i32 s19, s18, 31
	s_lshl_b64 s[24:25], s[18:19], 11
	s_add_u32 s34, s20, s24
	s_addc_u32 s35, s21, s25
	s_add_u32 s24, s2, s24
	s_addc_u32 s25, s3, s25
	global_load_dwordx4 v[84:87], v96, s[24:25]
	global_load_dwordx4 v[80:83], v96, s[24:25] offset:1024
	global_load_dwordx4 v[92:95], v96, s[34:35]
	global_load_dwordx4 v[88:91], v96, s[34:35] offset:1024

.LBB0_902:
	s_cmp_eq_u32 s80, 8
	s_mov_b64 s[4:5], -1
	s_cbranch_scc1 .LBB0_895
	s_and_b32 s56, s69, 7
	s_ashr_i32 s4, s69, 3
	s_lshr_b32 s5, s80, 2
	s_lshl_b32 s83, s56, 1
	s_add_i32 s83, s83, s5
	v_readfirstlane_b32 s85, v240
	s_ashr_i32 s5, s4, 31
	s_lshl_b32 s29, s81, 8
	s_ashr_i32 s82, s85, 6
	s_lshl_b64 s[34:35], s[4:5], 13
	s_ashr_i32 s6, s29, 31
	s_add_u32 s33, s34, s29
	s_addc_u32 s6, s35, s6
	s_lshl_b32 s34, s82, 5
	s_ashr_i32 s35, s34, 31
	s_add_u32 s46, s33, s34
	s_addc_u32 s47, s6, s35
	s_lshl_b64 s[34:35], s[46:47], 11
	s_add_u32 s6, s58, s34
	s_addc_u32 s33, s59, s35
	s_lshl_b32 s48, s83, 7
	s_add_u32 s34, s6, s48
	s_addc_u32 s35, s33, 0
	s_lshl_b64 s[4:5], s[4:5], 24
	s_add_u32 s6, s60, s4
	s_addc_u32 s33, s61, s5
	s_add_u32 s48, s6, s48
	s_addc_u32 s49, s33, 0
	s_add_u32 s6, s62, s4
	s_addc_u32 s33, s63, s5
	s_lshl_b32 s57, s56, 8
	s_add_u32 s50, s6, s57
	v_mov_b32_e32 v229, v1
	s_addc_u32 s51, s33, 0
	s_waitcnt lgkmcnt(0)
	v_lshl_add_u64 v[2:3], s[48:49], 0, v[228:229]
	s_lshl_b32 s48, s82, 3
	s_lshl_b32 s6, s82, 4
	s_ashr_i32 s49, s48, 31
	v_and_or_b32 v0, s6, 48, v245
	s_ashr_i32 s6, s85, 3
	v_lshl_add_u64 v[232:233], s[48:49], 1, v[2:3]
	s_and_b32 s48, s6, 0xffffffe0
	s_ashr_i32 s49, s48, 31
	s_lshl_b32 s6, s82, 10
	v_lshlrev_b32_e32 v0, 11, v0
	s_cmp_lg_u32 0, -1
	v_lshl_add_u64 v[2:3], s[50:51], 0, v[0:1]
	s_cselect_b32 s33, 0, 0
	v_lshl_add_u64 v[2:3], s[48:49], 1, v[2:3]
	v_mov_b32_e32 v231, v1
	s_add_i32 s86, s6, s33
	s_mov_b32 m0, s86
	s_nop 0
	global_load_lds_dwordx4 v[232:233], off
	v_lshl_add_u64 v[34:35], v[2:3], 0, v[230:231]
	s_add_i32 s87, s86, 0x6000
	s_mov_b32 m0, s87
	s_nop 0
	global_load_lds_dwordx4 v[34:35], off
	v_lshl_add_u64 v[2:3], v[34:35], 0, s[10:11]
	s_add_i32 s33, s86, 0x8000
	s_mov_b32 m0, s33
	s_nop 0
	global_load_lds_dwordx4 v[2:3], off
	v_lshl_add_u64 v[2:3], v[232:233], 0, s[12:13]
	s_add_i32 s33, s86, 0x2000
	s_mov_b32 m0, s33
	s_nop 0
	global_load_lds_dwordx4 v[2:3], off
	global_load_dwordx4 v[188:191], v252, s[34:35]
	global_load_dwordx4 v[184:187], v252, s[34:35] offset:32
	global_load_dwordx4 v[176:179], v252, s[34:35] offset:64
	global_load_dwordx4 v[168:171], v252, s[34:35] offset:96
	v_mov_b32_e32 v2, v1
	v_mov_b32_e32 v3, v1
	v_mov_b32_e32 v4, v1
	v_mov_b32_e32 v5, v1
	v_mov_b32_e32 v6, v1
	v_mov_b32_e32 v7, v1
	v_mov_b32_e32 v8, v1
	v_mov_b32_e32 v9, v1
	v_mov_b32_e32 v10, v1
	v_mov_b32_e32 v11, v1
	v_mov_b32_e32 v12, v1
	v_mov_b32_e32 v13, v1
	v_mov_b32_e32 v14, v1
	v_mov_b32_e32 v15, v1
	v_mov_b32_e32 v0, v1
	v_mov_b64_e32 v[16:17], v[14:15]
	v_mov_b64_e32 v[14:15], v[12:13]
	v_mov_b64_e32 v[12:13], v[10:11]
	v_mov_b64_e32 v[10:11], v[8:9]
	v_mov_b64_e32 v[8:9], v[6:7]
	v_mov_b64_e32 v[6:7], v[4:5]
	v_mov_b64_e32 v[4:5], v[2:3]
	v_mov_b64_e32 v[2:3], v[0:1]
	v_lshl_add_u64 v[18:19], v[232:233], 0, s[16:17]
	s_add_i32 s33, s86, 0x4000
	s_mov_b32 m0, s33
	s_nop 0
	global_load_lds_dwordx4 v[18:19], off
	s_waitcnt vmcnt(3) lgkmcnt(0)
	s_barrier
	ds_read_b128 v[36:39], v247
	s_addk_i32 s29, 0x100
	s_ashr_i32 s89, s29, 6
	s_cmp_gt_i32 s89, 4
	s_waitcnt vmcnt(3) lgkmcnt(0)
	v_mfma_f32_32x32x16_bf16 v[18:33], v[36:39], v[188:191], v[2:17]
	ds_read_b128 v[36:39], v247 offset:512
	s_waitcnt lgkmcnt(0)
	v_mfma_f32_32x32x16_bf16 v[2:17], v[36:39], v[188:191], v[2:17]
	ds_read_b128 v[36:39], v247 offset:2048
	s_waitcnt vmcnt(2) lgkmcnt(0)
	v_mfma_f32_32x32x16_bf16 v[18:33], v[36:39], v[184:187], v[18:33]
	ds_read_b128 v[36:39], v247 offset:2560
	s_waitcnt lgkmcnt(0)
	v_mfma_f32_32x32x16_bf16 v[2:17], v[36:39], v[184:187], v[2:17]
	ds_read_b128 v[36:39], v247 offset:4096
	s_waitcnt vmcnt(1) lgkmcnt(0)
	v_mfma_f32_32x32x16_bf16 v[18:33], v[36:39], v[176:179], v[18:33]
	ds_read_b128 v[36:39], v247 offset:4608
	s_waitcnt lgkmcnt(0)
	v_mfma_f32_32x32x16_bf16 v[2:17], v[36:39], v[176:179], v[2:17]
	ds_read_b128 v[36:39], v247 offset:6144
	s_waitcnt vmcnt(0) lgkmcnt(0)
	v_mfma_f32_32x32x16_bf16 v[18:33], v[36:39], v[168:171], v[18:33]
	ds_read_b128 v[36:39], v247 offset:6656
	s_waitcnt lgkmcnt(0)
	v_mfma_f32_32x32x16_bf16 v[2:17], v[36:39], v[168:171], v[2:17]
	s_nop 15
	s_nop 7
	s_cbranch_scc1 .LBB0_905
	s_sub_i32 s29, 4, s89
	s_ashr_i32 s33, s85, 7
	s_cmp_gt_i32 s29, s33
	s_cselect_b64 vcc, -1, 0
	s_nop 3
	v_cndmask_b32_e32 v33, v33, v238, vcc
	v_cndmask_b32_e32 v32, v32, v238, vcc
	v_cndmask_b32_e32 v31, v31, v238, vcc
	v_cndmask_b32_e32 v30, v30, v238, vcc
	v_cndmask_b32_e32 v29, v29, v238, vcc
	v_cndmask_b32_e32 v28, v28, v238, vcc
	v_cndmask_b32_e32 v27, v27, v238, vcc
	v_cndmask_b32_e32 v26, v26, v238, vcc
	v_cndmask_b32_e32 v25, v25, v238, vcc
	v_cndmask_b32_e32 v24, v24, v238, vcc
	v_cndmask_b32_e32 v23, v23, v238, vcc
	v_cndmask_b32_e32 v22, v22, v238, vcc
	v_cndmask_b32_e32 v21, v21, v238, vcc
	v_cndmask_b32_e32 v20, v20, v238, vcc
	v_cndmask_b32_e32 v19, v19, v238, vcc
	v_cndmask_b32_e32 v18, v18, v238, vcc
	v_cndmask_b32_e32 v17, v17, v238, vcc
	v_cndmask_b32_e32 v16, v16, v238, vcc
	v_cndmask_b32_e32 v15, v15, v238, vcc
	v_cndmask_b32_e32 v14, v14, v238, vcc
	v_cndmask_b32_e32 v13, v13, v238, vcc
	v_cndmask_b32_e32 v12, v12, v238, vcc
	v_cndmask_b32_e32 v11, v11, v238, vcc
	v_cndmask_b32_e32 v10, v10, v238, vcc
	v_cndmask_b32_e32 v9, v9, v238, vcc
	v_cndmask_b32_e32 v8, v8, v238, vcc
	v_cndmask_b32_e32 v7, v7, v238, vcc
	v_cndmask_b32_e32 v6, v6, v238, vcc
	v_cndmask_b32_e32 v5, v5, v238, vcc
	v_cndmask_b32_e32 v4, v4, v238, vcc
	v_cndmask_b32_e32 v3, v3, v238, vcc
	v_cndmask_b32_e32 v2, v2, v238, vcc
.LBB0_905:
	v_max3_f32 v0, v18, v19, v2
	v_max3_f32 v36, v20, v21, v3
	s_and_b32 s29, s85, 0x3fffffc0
	v_max3_f32 v0, v0, v4, v5
	v_max3_f32 v36, v36, v24, v25
	s_lshl_b32 s29, s29, 2
	v_max3_f32 v0, v0, v22, v23
	v_max3_f32 v36, v36, v8, v9
	s_add_i32 s84, s29, 0
	v_max3_f32 v0, v0, v6, v7
	v_max3_f32 v36, v36, v28, v29
	s_add_i32 s84, s84, 0x12000
	v_max3_f32 v0, v0, v26, v27
	v_max3_f32 v36, v36, v12, v13
	s_cmp_lg_u32 0, -1
	v_max3_f32 v0, v0, v10, v11
	v_max3_f32 v36, v36, v32, v33
	s_mov_b32 s91, 0
	v_max3_f32 v0, v0, v30, v31
	v_max3_f32 v36, v36, v16, v17
	v_lshl_add_u32 v229, v244, 2, s84
	v_max3_f32 v0, v0, v14, v15
	s_nop 0
	v_max_f32_e32 v0, v0, v36
	s_nop 0
	v_mov_b32_e32 v36, v0
	s_nop 1
	v_permlane32_swap_b32_e32 v0, v36
	v_max_f32_e32 v0, v0, v36
	s_nop 0
	v_add_f32_e32 v231, v1, v0
	v_sub_f32_e32 v2, v2, v0
	v_sub_f32_e32 v3, v3, v0
	v_sub_f32_e32 v18, v18, v0
	v_sub_f32_e32 v19, v19, v0
	v_sub_f32_e32 v20, v20, v0
	s_nop 0
	v_xor_b32_e32 v80, 0x80000000, v231
	v_mov_b32_e32 v81, v80
	v_mov_b32_e32 v82, v80
	v_mov_b32_e32 v83, v80
	v_mov_b32_e32 v84, v80
	v_mov_b32_e32 v85, v80
	v_mov_b32_e32 v86, v80
	v_mov_b32_e32 v87, v80
	v_mov_b32_e32 v88, v80
	v_mov_b32_e32 v89, v80
	v_mov_b32_e32 v90, v80
	v_mov_b32_e32 v91, v80
	v_mov_b32_e32 v92, v80
	v_mov_b32_e32 v93, v80
	v_mov_b32_e32 v94, v80
	v_mov_b32_e32 v95, v80
	s_waitcnt vmcnt(0) lgkmcnt(0)
	s_barrier
	v_exp_f32_e32 v96, v2
	v_exp_f32_e32 v97, v3
	v_lshl_add_u64 v[2:3], v[232:233], 0, s[18:19]
	s_mov_b32 m0, s86
	s_nop 0
	global_load_lds_dwordx4 v[2:3], off
	s_cselect_b32 s29, 0, 0
	s_add_i32 s6, s29, s6
	v_lshl_add_u64 v[2:3], v[34:35], 0, s[12:13]
	s_add_i32 s29, s6, 0xa000
	s_mov_b32 m0, s29
	s_nop 0
	global_load_lds_dwordx4 v[2:3], off
	v_lshl_add_u64 v[2:3], v[34:35], 0, s[20:21]
	s_add_i32 s6, s6, 0xc000
	s_mov_b32 m0, s6
	s_nop 0
	global_load_lds_dwordx4 v[2:3], off
	ds_read_b128 v[220:223], v247 offset:8192
	ds_read_b128 v[216:219], v247 offset:8704
	ds_read_b128 v[212:215], v247 offset:10240
	ds_read_b128 v[208:211], v247 offset:10752
	ds_read_b128 v[204:207], v247 offset:12288
	ds_read_b128 v[200:203], v247 offset:12800
	ds_read_b128 v[196:199], v247 offset:14336
	ds_read_b128 v[192:195], v247 offset:14848
	v_sub_f32_e32 v4, v4, v0
	v_sub_f32_e32 v21, v21, v0
	v_sub_f32_e32 v5, v5, v0
	v_sub_f32_e32 v22, v22, v0
	v_sub_f32_e32 v6, v6, v0
	v_sub_f32_e32 v23, v23, v0
	v_sub_f32_e32 v7, v7, v0
	v_sub_f32_e32 v24, v24, v0
	v_sub_f32_e32 v8, v8, v0
	v_sub_f32_e32 v25, v25, v0
	v_sub_f32_e32 v9, v9, v0
	v_sub_f32_e32 v26, v26, v0
	v_sub_f32_e32 v10, v10, v0
	v_sub_f32_e32 v27, v27, v0
	v_sub_f32_e32 v11, v11, v0
	v_sub_f32_e32 v28, v28, v0
	v_sub_f32_e32 v12, v12, v0
	v_sub_f32_e32 v29, v29, v0
	v_sub_f32_e32 v13, v13, v0
	v_sub_f32_e32 v30, v30, v0
	v_sub_f32_e32 v14, v14, v0
	v_sub_f32_e32 v31, v31, v0
	v_sub_f32_e32 v15, v15, v0
	v_sub_f32_e32 v32, v32, v0
	v_sub_f32_e32 v16, v16, v0
	v_sub_f32_e32 v33, v33, v0
	v_sub_f32_e32 v0, v17, v0
	v_exp_f32_e32 v112, v18
	v_exp_f32_e32 v113, v19
	v_exp_f32_e32 v114, v20
	v_exp_f32_e32 v115, v21
	v_exp_f32_e32 v116, v22
	v_exp_f32_e32 v117, v23
	v_exp_f32_e32 v118, v24
	v_exp_f32_e32 v119, v25
	v_exp_f32_e32 v120, v26
	v_exp_f32_e32 v121, v27
	v_exp_f32_e32 v122, v28
	v_exp_f32_e32 v123, v29
	v_exp_f32_e32 v124, v30
	v_exp_f32_e32 v125, v31
	v_exp_f32_e32 v126, v32
	v_exp_f32_e32 v127, v33
	v_exp_f32_e32 v98, v4
	v_exp_f32_e32 v99, v5
	v_exp_f32_e32 v100, v6
	v_exp_f32_e32 v101, v7
	v_exp_f32_e32 v102, v8
	v_exp_f32_e32 v103, v9
	v_exp_f32_e32 v104, v10
	v_exp_f32_e32 v105, v11
	v_exp_f32_e32 v106, v12
	v_exp_f32_e32 v107, v13
	v_exp_f32_e32 v108, v14
	v_exp_f32_e32 v109, v15
	v_exp_f32_e32 v110, v16
	v_exp_f32_e32 v111, v0
	s_waitcnt vmcnt(3) lgkmcnt(0)
	s_barrier
	s_cmp_lt_i32 s89, 7
	s_cbranch_scc1 .LBB0_921
	s_add_i32 s88, s89, -5
	s_or_b32 s29, s4, s57
	s_lshl_b64 s[34:35], s[48:49], 1
	s_add_u32 s34, s29, s34
	s_addc_u32 s35, s5, s35
	s_lshl_b32 s29, s85, 9
	s_and_b32 s29, s29, 0x18000
	v_lshlrev_b32_e32 v0, 10, v245
	v_lshl_or_b32 v0, v0, 1, s29
	v_lshl_add_u64 v[2:3], s[34:35], 0, v[0:1]
	v_mov_b32_e32 v14, v1
	v_mov_b32_e32 v15, v1
	v_lshl_add_u64 v[234:235], v[226:227], 0, v[2:3]
	v_mov_b32_e32 v0, v1
	v_mov_b32_e32 v2, v1
	v_mov_b32_e32 v3, v1
	v_mov_b32_e32 v4, v1
	v_mov_b32_e32 v5, v1
	v_mov_b32_e32 v6, v1
	v_mov_b32_e32 v7, v1
	v_mov_b32_e32 v8, v1
	v_mov_b32_e32 v9, v1
	v_mov_b32_e32 v10, v1
	v_mov_b32_e32 v11, v1
	v_mov_b32_e32 v12, v1
	v_mov_b32_e32 v13, v1
	v_mov_b64_e32 v[78:79], v[14:15]
	v_mov_b64_e32 v[62:63], v[14:15]
	v_mov_b64_e32 v[46:47], v[14:15]
	v_mov_b64_e32 v[30:31], v[14:15]
	s_mov_b32 s6, 1
	s_mov_b32 s33, 0
	s_movk_i32 s91, 0x4000
	s_movk_i32 s34, 0x2000
	v_mov_b32_e32 v251, 0
	s_mov_b64 s[50:51], 0
	v_mov_b64_e32 v[76:77], v[12:13]
	v_mov_b64_e32 v[74:75], v[10:11]
	v_mov_b64_e32 v[72:73], v[8:9]
	v_mov_b64_e32 v[70:71], v[6:7]
	v_mov_b64_e32 v[68:69], v[4:5]
	v_mov_b64_e32 v[66:67], v[2:3]
	v_mov_b64_e32 v[64:65], v[0:1]
	v_mov_b64_e32 v[60:61], v[12:13]
	v_mov_b64_e32 v[58:59], v[10:11]
	v_mov_b64_e32 v[56:57], v[8:9]
	v_mov_b64_e32 v[54:55], v[6:7]
	v_mov_b64_e32 v[52:53], v[4:5]
	v_mov_b64_e32 v[50:51], v[2:3]
	v_mov_b64_e32 v[48:49], v[0:1]
	v_mov_b64_e32 v[44:45], v[12:13]
	v_mov_b64_e32 v[42:43], v[10:11]
	v_mov_b64_e32 v[40:41], v[8:9]
	v_mov_b64_e32 v[38:39], v[6:7]
	v_mov_b64_e32 v[36:37], v[4:5]
	v_mov_b64_e32 v[34:35], v[2:3]
	v_mov_b64_e32 v[32:33], v[0:1]
	v_mov_b64_e32 v[28:29], v[12:13]
	v_mov_b64_e32 v[26:27], v[10:11]
	v_mov_b64_e32 v[24:25], v[8:9]
	v_mov_b64_e32 v[22:23], v[6:7]
	v_mov_b64_e32 v[20:21], v[4:5]
	v_mov_b64_e32 v[18:19], v[2:3]
	v_mov_b64_e32 v[16:17], v[0:1]
.LBB0_907:
	s_lshl_b32 s29, s33, 1
	v_add_u32_e32 v236, s29, v248
	ds_read_b64_tr_b16 v[2:3], v236 offset:24576
	ds_read_b64_tr_b16 v[4:5], v236 offset:25088
	s_waitcnt lgkmcnt(9)
	v_mfma_f32_32x32x16_bf16 v[144:159], v[220:223], v[188:191], v[80:95]
	v_add_f32_e32 v0, v112, v113
	v_add_f32_e32 v0, v114, v0
	v_add_f32_e32 v0, v115, v0
	v_add_f32_e32 v0, v116, v0
	v_add_f32_e32 v0, v117, v0
	v_cvt_pk_bf16_f32 v180, v112, v113
	v_cvt_pk_bf16_f32 v181, v114, v115
	ds_read_b64_tr_b16 v[6:7], v236 offset:28672
	ds_read_b64_tr_b16 v[8:9], v236 offset:29184
	s_waitcnt lgkmcnt(10)
	v_mfma_f32_32x32x16_bf16 v[128:143], v[216:219], v[188:191], v[80:95]
	v_add_f32_e32 v0, v118, v0
	v_add_f32_e32 v0, v119, v0
	v_add_f32_e32 v0, v120, v0
	v_add_f32_e32 v0, v121, v0
	v_cvt_pk_bf16_f32 v182, v116, v117
	v_cvt_pk_bf16_f32 v183, v118, v119
	ds_read_b64_tr_b16 v[10:11], v236 offset:25600
	ds_read_b64_tr_b16 v[12:13], v236 offset:26112
	s_waitcnt lgkmcnt(11)
	v_mfma_f32_32x32x16_bf16 v[144:159], v[212:215], v[184:187], v[144:159]
	v_add_f32_e32 v0, v122, v0
	v_add_f32_e32 v0, v123, v0
	v_add_f32_e32 v0, v124, v0
	v_add_f32_e32 v0, v125, v0
	v_cvt_pk_bf16_f32 v172, v120, v121
	v_cvt_pk_bf16_f32 v173, v122, v123
	ds_read_b64_tr_b16 v[112:113], v236 offset:29696
	ds_read_b64_tr_b16 v[114:115], v236 offset:30208
	s_waitcnt lgkmcnt(12)
	v_mfma_f32_32x32x16_bf16 v[128:143], v[208:211], v[184:187], v[128:143]
	v_add_f32_e32 v0, v126, v0
	v_add_f32_e32 v0, v127, v0
	v_add_f32_e32 v0, v96, v0
	v_add_f32_e32 v0, v97, v0
	v_cvt_pk_bf16_f32 v174, v124, v125
	v_cvt_pk_bf16_f32 v175, v126, v127
	s_waitcnt lgkmcnt(11)
	v_mfma_f32_32x32x16_bf16 v[144:159], v[204:207], v[176:179], v[144:159]
	v_add_f32_e32 v0, v98, v0
	v_add_f32_e32 v0, v99, v0
	v_add_f32_e32 v0, v100, v0
	v_add_f32_e32 v0, v101, v0
	v_cvt_pk_bf16_f32 v164, v96, v97
	v_cvt_pk_bf16_f32 v165, v98, v99
	s_waitcnt lgkmcnt(10)
	v_mfma_f32_32x32x16_bf16 v[128:143], v[200:203], v[176:179], v[128:143]
	v_add_f32_e32 v0, v102, v0
	v_add_f32_e32 v0, v103, v0
	v_add_f32_e32 v0, v104, v0
	v_add_f32_e32 v0, v105, v0
	v_cvt_pk_bf16_f32 v166, v100, v101
	v_cvt_pk_bf16_f32 v167, v102, v103
	s_waitcnt lgkmcnt(9)
	v_mfma_f32_32x32x16_bf16 v[144:159], v[196:199], v[168:171], v[144:159]
	v_add_f32_e32 v0, v106, v0
	v_add_f32_e32 v0, v107, v0
	v_add_f32_e32 v0, v108, v0
	v_add_f32_e32 v0, v109, v0
	v_cvt_pk_bf16_f32 v160, v104, v105
	v_cvt_pk_bf16_f32 v161, v106, v107
	s_waitcnt lgkmcnt(8)
	v_mfma_f32_32x32x16_bf16 v[128:143], v[192:195], v[168:171], v[128:143]
	v_add_f32_e32 v0, v110, v0
	v_add_f32_e32 v0, v111, v0
	v_add_f32_e32 v0, 0, v0
	v_cvt_pk_bf16_f32 v162, v108, v109
	v_cvt_pk_bf16_f32 v163, v110, v111
	v_lshl_add_u64 v[212:213], v[232:233], 0, s[50:51]
	v_lshl_add_u64 v[14:15], v[212:213], 0, s[22:23]
	s_add_i32 s29, s34, s86
	s_mov_b32 m0, s29
	s_nop 0
	global_load_lds_dwordx4 v[14:15], off
	v_lshl_add_u64 v[14:15], v[234:235], 0, s[50:51]
	v_lshl_add_u64 v[96:97], v[14:15], 0, s[24:25]
	s_lshl_b32 s29, s91, 1
	s_add_i32 s29, s29, s87
	s_mov_b32 m0, s29
	s_nop 0
	global_load_lds_dwordx4 v[96:97], off
	v_lshl_add_u64 v[96:97], v[14:15], 0, s[26:27]
	s_addk_i32 s29, 0x2000
	s_mov_b32 m0, s29
	s_nop 0
	global_load_lds_dwordx4 v[96:97], off
	v_max_f32_e32 v96, v145, v145
	v_max_f32_e32 v97, v144, v144
	v_max_f32_e32 v96, v97, v96
	v_max3_f32 v97, v146, v147, v129
	v_max3_f32 v96, v96, v128, v130
	v_max3_f32 v96, v96, v131, v148
	v_max3_f32 v97, v97, v150, v151
	v_max3_f32 v96, v96, v149, v132
	v_max3_f32 v97, v97, v134, v135
	v_max3_f32 v96, v96, v133, v152
	v_max3_f32 v97, v97, v154, v155
	v_max3_f32 v96, v96, v153, v136
	v_max3_f32 v97, v97, v138, v139
	v_max3_f32 v96, v96, v137, v156
	v_max3_f32 v97, v97, v158, v159
	v_max3_f32 v96, v96, v157, v140
	v_max3_f32 v97, v97, v142, v143
	v_max3_f32 v96, v96, v141, v97
	v_mov_b32_e32 v97, v96
	s_nop 1
	v_permlane32_swap_b32_e32 v96, v97
	v_max_f32_e32 v97, v97, v97
	v_max_f32_e32 v96, v96, v96
	v_max_f32_e32 v96, v96, v97
	v_cmp_lt_f32_e32 vcc, s73, v96
	s_cmp_lg_u64 vcc, 0
	v_add_f32_e32 v0, v251, v0
	s_cselect_b64 s[52:53], -1, 0
	s_cbranch_vccnz .LBB0_915

.LBB0_910:
	s_add_i32 s29, s91, 0x2000
	s_cmpk_lg_i32 s91, 0x4000
	s_cselect_b32 s90, s29, 0
	s_lshl_b32 s29, s34, 1
	v_add_u32_e32 v214, s29, v248
	ds_read_b64_tr_b16 v[192:193], v214 offset:24576
	ds_read_b64_tr_b16 v[194:195], v214 offset:25088
	s_waitcnt lgkmcnt(9)
	v_mfma_f32_32x32x16_bf16 v[112:127], v[96:99], v[188:191], v[80:95]
	v_add_f32_e32 v100, v144, v145
	v_add_f32_e32 v100, v146, v100
	v_add_f32_e32 v100, v147, v100
	v_add_f32_e32 v100, v148, v100
	v_add_f32_e32 v100, v149, v100
	v_cvt_pk_bf16_f32 v180, v144, v145
	v_cvt_pk_bf16_f32 v181, v146, v147
	ds_read_b64_tr_b16 v[144:145], v214 offset:28672
	ds_read_b64_tr_b16 v[146:147], v214 offset:29184
	v_add_f32_e32 v96, v150, v100
	v_add_f32_e32 v96, v151, v96
	v_add_f32_e32 v96, v152, v96
	v_add_f32_e32 v160, v153, v96
	s_waitcnt lgkmcnt(10)
	v_mfma_f32_32x32x16_bf16 v[96:111], v[208:211], v[188:191], v[80:95]
	v_cvt_pk_bf16_f32 v182, v148, v149
	v_cvt_pk_bf16_f32 v183, v150, v151
	ds_read_b64_tr_b16 v[148:149], v214 offset:25600
	ds_read_b64_tr_b16 v[150:151], v214 offset:26112
	s_waitcnt lgkmcnt(11)
	v_mfma_f32_32x32x16_bf16 v[112:127], v[204:207], v[184:187], v[112:127]
	v_add_f32_e32 v160, v154, v160
	v_add_f32_e32 v160, v155, v160
	v_add_f32_e32 v160, v156, v160
	v_add_f32_e32 v160, v157, v160
	v_cvt_pk_bf16_f32 v172, v152, v153
	v_cvt_pk_bf16_f32 v173, v154, v155
	ds_read_b64_tr_b16 v[152:153], v214 offset:29696
	ds_read_b64_tr_b16 v[154:155], v214 offset:30208
	s_waitcnt lgkmcnt(12)
	v_mfma_f32_32x32x16_bf16 v[96:111], v[196:199], v[184:187], v[96:111]
	v_add_f32_e32 v160, v158, v160
	v_add_f32_e32 v160, v159, v160
	v_add_f32_e32 v160, v128, v160
	v_add_f32_e32 v160, v129, v160
	v_cvt_pk_bf16_f32 v174, v156, v157
	v_cvt_pk_bf16_f32 v175, v158, v159
	s_waitcnt lgkmcnt(11)
	v_mfma_f32_32x32x16_bf16 v[112:127], v[200:203], v[176:179], v[112:127]
	v_add_f32_e32 v156, v130, v160
	v_add_f32_e32 v156, v131, v156
	v_add_f32_e32 v156, v132, v156
	v_add_f32_e32 v156, v133, v156
	v_cvt_pk_bf16_f32 v164, v128, v129
	v_cvt_pk_bf16_f32 v165, v130, v131
	s_waitcnt lgkmcnt(10)
	v_mfma_f32_32x32x16_bf16 v[96:111], v[6:9], v[176:179], v[96:111]
	v_add_f32_e32 v128, v134, v156
	v_add_f32_e32 v128, v135, v128
	v_add_f32_e32 v128, v136, v128
	v_add_f32_e32 v128, v137, v128
	v_cvt_pk_bf16_f32 v166, v132, v133
	v_cvt_pk_bf16_f32 v167, v134, v135
	s_waitcnt lgkmcnt(9)
	v_mfma_f32_32x32x16_bf16 v[112:127], v[10:13], v[168:171], v[112:127]
	v_add_f32_e32 v6, v138, v128
	v_add_f32_e32 v6, v139, v6
	v_add_f32_e32 v6, v140, v6
	v_add_f32_e32 v6, v141, v6
	v_cvt_pk_bf16_f32 v160, v136, v137
	v_cvt_pk_bf16_f32 v161, v138, v139
	s_waitcnt lgkmcnt(8)
	v_mfma_f32_32x32x16_bf16 v[96:111], v[2:5], v[168:171], v[96:111]
	v_add_f32_e32 v6, v142, v6
	v_add_f32_e32 v6, v143, v6
	v_add_f32_e32 v6, 0, v6
	v_cvt_pk_bf16_f32 v162, v140, v141
	v_cvt_pk_bf16_f32 v163, v142, v143
	v_lshl_add_u64 v[2:3], v[212:213], 0, s[36:37]
	s_add_i32 s29, s91, s86
	s_mov_b32 m0, s29
	s_nop 0
	global_load_lds_dwordx4 v[2:3], off
	v_lshl_add_u64 v[2:3], v[14:15], 0, s[38:39]
	s_lshl_b32 s29, s90, 1
	s_add_i32 s29, s29, s87
	s_mov_b32 m0, s29
	s_nop 0
	global_load_lds_dwordx4 v[2:3], off
	v_lshl_add_u64 v[2:3], v[14:15], 0, s[40:41]
	s_addk_i32 s29, 0x2000
	s_mov_b32 m0, s29
	s_nop 0
	global_load_lds_dwordx4 v[2:3], off
	v_max_f32_e32 v2, v113, v113
	v_max_f32_e32 v3, v112, v112
	v_max_f32_e32 v2, v3, v2
	v_max3_f32 v3, v114, v115, v97
	v_max3_f32 v2, v2, v96, v98
	v_max3_f32 v2, v2, v99, v116
	v_max3_f32 v3, v3, v118, v119
	v_max3_f32 v2, v2, v117, v100
	v_max3_f32 v3, v3, v102, v103
	v_max3_f32 v2, v2, v101, v120
	v_max3_f32 v3, v3, v122, v123
	v_max3_f32 v2, v2, v121, v104
	v_max3_f32 v3, v3, v106, v107
	v_max3_f32 v2, v2, v105, v124
	v_max3_f32 v3, v3, v126, v127
	v_max3_f32 v2, v2, v125, v108
	v_max3_f32 v3, v3, v110, v111
	v_add_f32_e32 v251, v0, v6
	v_max3_f32 v0, v2, v109, v3
	v_mov_b32_e32 v2, v0
	s_nop 1
	v_permlane32_swap_b32_e32 v0, v2
	v_max_f32_e32 v2, v2, v2
	v_max_f32_e32 v0, v0, v0
	v_max_f32_e32 v0, v0, v2
	v_cmp_lt_f32_e32 vcc, s73, v0
	s_cmp_lg_u64 vcc, 0
	s_cselect_b64 s[52:53], -1, 0
	s_cbranch_vccnz .LBB0_918

.LBB0_926:
	s_lshl_b32 s4, s91, 1
	v_add_u32_e32 v253, s4, v248
	ds_read_b64_tr_b16 v[2:3], v253 offset:24576
	ds_read_b64_tr_b16 v[4:5], v253 offset:25088
	s_waitcnt lgkmcnt(9)
	v_mfma_f32_32x32x16_bf16 v[144:159], v[220:223], v[188:191], v[80:95]
	v_add_f32_e32 v0, v112, v113
	v_add_f32_e32 v0, v114, v0
	v_add_f32_e32 v0, v115, v0
	v_add_f32_e32 v0, v116, v0
	v_add_f32_e32 v0, v117, v0
	v_cvt_pk_bf16_f32 v180, v112, v113
	v_cvt_pk_bf16_f32 v181, v114, v115
	ds_read_b64_tr_b16 v[6:7], v253 offset:28672
	ds_read_b64_tr_b16 v[8:9], v253 offset:29184
	s_waitcnt lgkmcnt(10)
	v_mfma_f32_32x32x16_bf16 v[128:143], v[216:219], v[188:191], v[80:95]
	v_add_f32_e32 v0, v118, v0
	v_add_f32_e32 v0, v119, v0
	v_add_f32_e32 v0, v120, v0
	v_add_f32_e32 v0, v121, v0
	v_cvt_pk_bf16_f32 v182, v116, v117
	v_cvt_pk_bf16_f32 v183, v118, v119
	ds_read_b64_tr_b16 v[10:11], v253 offset:25600
	ds_read_b64_tr_b16 v[12:13], v253 offset:26112
	s_waitcnt lgkmcnt(11)
	v_mfma_f32_32x32x16_bf16 v[144:159], v[212:215], v[184:187], v[144:159]
	v_add_f32_e32 v0, v122, v0
	v_add_f32_e32 v0, v123, v0
	v_add_f32_e32 v0, v124, v0
	v_add_f32_e32 v0, v125, v0
	v_cvt_pk_bf16_f32 v172, v120, v121
	v_cvt_pk_bf16_f32 v173, v122, v123
	ds_read_b64_tr_b16 v[112:113], v253 offset:29696
	ds_read_b64_tr_b16 v[114:115], v253 offset:30208
	s_waitcnt lgkmcnt(12)
	v_mfma_f32_32x32x16_bf16 v[128:143], v[208:211], v[184:187], v[128:143]
	v_add_f32_e32 v0, v126, v0
	v_add_f32_e32 v0, v127, v0
	v_add_f32_e32 v0, v96, v0
	v_add_f32_e32 v0, v97, v0
	v_cvt_pk_bf16_f32 v174, v124, v125
	v_cvt_pk_bf16_f32 v175, v126, v127
	s_waitcnt lgkmcnt(11)
	v_mfma_f32_32x32x16_bf16 v[144:159], v[204:207], v[176:179], v[144:159]
	v_add_f32_e32 v0, v98, v0
	v_add_f32_e32 v0, v99, v0
	v_add_f32_e32 v0, v100, v0
	v_add_f32_e32 v0, v101, v0
	v_cvt_pk_bf16_f32 v164, v96, v97
	v_cvt_pk_bf16_f32 v165, v98, v99
	s_waitcnt lgkmcnt(10)
	v_mfma_f32_32x32x16_bf16 v[128:143], v[200:203], v[176:179], v[128:143]
	v_add_f32_e32 v0, v102, v0
	v_add_f32_e32 v0, v103, v0
	v_add_f32_e32 v0, v104, v0
	v_add_f32_e32 v0, v105, v0
	v_cvt_pk_bf16_f32 v166, v100, v101
	v_cvt_pk_bf16_f32 v167, v102, v103
	s_waitcnt lgkmcnt(9)
	v_mfma_f32_32x32x16_bf16 v[144:159], v[196:199], v[168:171], v[144:159]
	v_add_f32_e32 v0, v106, v0
	v_add_f32_e32 v0, v107, v0
	v_add_f32_e32 v0, v108, v0
	v_add_f32_e32 v0, v109, v0
	v_cvt_pk_bf16_f32 v160, v104, v105
	v_cvt_pk_bf16_f32 v161, v106, v107
	s_waitcnt lgkmcnt(8)
	v_mfma_f32_32x32x16_bf16 v[128:143], v[192:195], v[168:171], v[128:143]
	v_add_f32_e32 v0, v110, v0
	v_add_f32_e32 v0, v111, v0
	v_add_f32_e32 v0, 0, v0
	v_cvt_pk_bf16_f32 v162, v108, v109
	v_cvt_pk_bf16_f32 v163, v110, v111
	s_add_i32 s4, s54, 1
	s_cmp_ge_i32 s4, s89
	s_cselect_b64 s[48:49], -1, 0
	s_and_b64 vcc, exec, s[48:49]
	v_lshl_add_u64 v[236:237], v[232:233], 0, s[50:51]
	s_cbranch_vccnz .LBB0_928
	s_add_i32 s4, s90, s86
	v_lshl_add_u64 v[96:97], v[236:237], 0, s[18:19]
	s_mov_b32 m0, s4
	s_nop 0
	global_load_lds_dwordx4 v[96:97], off
.LBB0_928:
	v_lshl_add_u64 v[234:235], v[14:15], 0, s[50:51]
	s_lshl_b32 s96, s92, 1
	v_lshl_add_u64 v[96:97], v[234:235], 0, s[42:43]
	s_add_i32 s4, s96, s87
	s_mov_b32 m0, s4
	s_nop 0
	global_load_lds_dwordx4 v[96:97], off
	v_lshl_add_u64 v[96:97], v[234:235], 0, s[44:45]
	s_add_i32 s5, s4, 0x2000
	s_add_i32 s6, s95, s54
	s_mov_b32 m0, s5
	s_nop 0
	global_load_lds_dwordx4 v[96:97], off
	s_add_i32 s4, s6, 2
	s_cmp_lt_i32 s4, 0
	s_cbranch_scc1 .LBB0_930
	s_cmp_gt_i32 s4, s94
	s_cselect_b64 vcc, -1, 0
	v_cndmask_b32_e32 v159, v159, v238, vcc
	v_cndmask_b32_e32 v158, v158, v238, vcc
	v_cndmask_b32_e32 v157, v157, v238, vcc
	v_cndmask_b32_e32 v156, v156, v238, vcc
	v_cndmask_b32_e32 v155, v155, v238, vcc
	v_cndmask_b32_e32 v154, v154, v238, vcc
	v_cndmask_b32_e32 v153, v153, v238, vcc
	v_cndmask_b32_e32 v152, v152, v238, vcc
	v_cndmask_b32_e32 v151, v151, v238, vcc
	v_cndmask_b32_e32 v150, v150, v238, vcc
	v_cndmask_b32_e32 v149, v149, v238, vcc
	v_cndmask_b32_e32 v148, v148, v238, vcc
	v_cndmask_b32_e32 v147, v147, v238, vcc
	v_cndmask_b32_e32 v146, v146, v238, vcc
	v_cndmask_b32_e32 v145, v145, v238, vcc
	v_cndmask_b32_e32 v144, v144, v238, vcc
	v_cndmask_b32_e32 v143, v143, v238, vcc
	v_cndmask_b32_e32 v142, v142, v238, vcc
	v_cndmask_b32_e32 v141, v141, v238, vcc
	v_cndmask_b32_e32 v140, v140, v238, vcc
	v_cndmask_b32_e32 v139, v139, v238, vcc
	v_cndmask_b32_e32 v138, v138, v238, vcc
	v_cndmask_b32_e32 v137, v137, v238, vcc
	v_cndmask_b32_e32 v136, v136, v238, vcc
	v_cndmask_b32_e32 v135, v135, v238, vcc
	v_cndmask_b32_e32 v134, v134, v238, vcc
	v_cndmask_b32_e32 v133, v133, v238, vcc
	v_cndmask_b32_e32 v132, v132, v238, vcc
	v_cndmask_b32_e32 v131, v131, v238, vcc
	v_cndmask_b32_e32 v130, v130, v238, vcc
	v_cndmask_b32_e32 v129, v129, v238, vcc
	v_cndmask_b32_e32 v128, v128, v238, vcc

.LBB0_939:
	s_lshl_b32 s4, s90, 1
	v_add_u32_e32 v253, s4, v248
	ds_read_b64_tr_b16 v[2:3], v253 offset:24576
	ds_read_b64_tr_b16 v[4:5], v253 offset:25088
	s_waitcnt lgkmcnt(9)
	v_mfma_f32_32x32x16_bf16 v[112:127], v[220:223], v[188:191], v[80:95]
	v_add_f32_e32 v6, v144, v145
	v_add_f32_e32 v6, v146, v6
	v_add_f32_e32 v6, v147, v6
	v_add_f32_e32 v6, v148, v6
	v_add_f32_e32 v10, v149, v6
	v_cvt_pk_bf16_f32 v180, v144, v145
	v_cvt_pk_bf16_f32 v181, v146, v147
	ds_read_b64_tr_b16 v[6:7], v253 offset:28672
	ds_read_b64_tr_b16 v[8:9], v253 offset:29184
	s_waitcnt lgkmcnt(10)
	v_mfma_f32_32x32x16_bf16 v[96:111], v[216:219], v[188:191], v[80:95]
	v_add_f32_e32 v10, v150, v10
	v_add_f32_e32 v10, v151, v10
	v_add_f32_e32 v10, v152, v10
	v_add_f32_e32 v144, v153, v10
	v_cvt_pk_bf16_f32 v182, v148, v149
	v_cvt_pk_bf16_f32 v183, v150, v151
	ds_read_b64_tr_b16 v[10:11], v253 offset:25600
	ds_read_b64_tr_b16 v[12:13], v253 offset:26112
	s_waitcnt lgkmcnt(11)
	v_mfma_f32_32x32x16_bf16 v[112:127], v[212:215], v[184:187], v[112:127]
	v_add_f32_e32 v144, v154, v144
	v_add_f32_e32 v144, v155, v144
	v_add_f32_e32 v144, v156, v144
	v_add_f32_e32 v148, v157, v144
	v_cvt_pk_bf16_f32 v172, v152, v153
	v_cvt_pk_bf16_f32 v173, v154, v155
	ds_read_b64_tr_b16 v[144:145], v253 offset:29696
	ds_read_b64_tr_b16 v[146:147], v253 offset:30208
	s_waitcnt lgkmcnt(12)
	v_mfma_f32_32x32x16_bf16 v[96:111], v[208:211], v[184:187], v[96:111]
	v_add_f32_e32 v148, v158, v148
	v_add_f32_e32 v148, v159, v148
	v_add_f32_e32 v148, v128, v148
	v_add_f32_e32 v148, v129, v148
	v_cvt_pk_bf16_f32 v174, v156, v157
	v_cvt_pk_bf16_f32 v175, v158, v159
	s_waitcnt lgkmcnt(11)
	v_mfma_f32_32x32x16_bf16 v[112:127], v[204:207], v[176:179], v[112:127]
	v_add_f32_e32 v148, v130, v148
	v_add_f32_e32 v148, v131, v148
	v_add_f32_e32 v148, v132, v148
	v_add_f32_e32 v148, v133, v148
	v_cvt_pk_bf16_f32 v164, v128, v129
	v_cvt_pk_bf16_f32 v165, v130, v131
	s_waitcnt lgkmcnt(10)
	v_mfma_f32_32x32x16_bf16 v[96:111], v[200:203], v[176:179], v[96:111]
	v_add_f32_e32 v128, v134, v148
	v_add_f32_e32 v128, v135, v128
	v_add_f32_e32 v128, v136, v128
	v_add_f32_e32 v128, v137, v128
	v_cvt_pk_bf16_f32 v166, v132, v133
	v_cvt_pk_bf16_f32 v167, v134, v135
	s_waitcnt lgkmcnt(9)
	v_mfma_f32_32x32x16_bf16 v[112:127], v[196:199], v[168:171], v[112:127]
	v_add_f32_e32 v128, v138, v128
	v_add_f32_e32 v128, v139, v128
	v_add_f32_e32 v128, v140, v128
	v_add_f32_e32 v128, v141, v128
	v_cvt_pk_bf16_f32 v160, v136, v137
	v_cvt_pk_bf16_f32 v161, v138, v139
	s_waitcnt lgkmcnt(8)
	v_mfma_f32_32x32x16_bf16 v[96:111], v[192:195], v[168:171], v[96:111]
	v_add_f32_e32 v128, v142, v128
	v_add_f32_e32 v128, v143, v128
	v_add_f32_e32 v128, 0, v128
	v_cvt_pk_bf16_f32 v162, v140, v141
	v_cvt_pk_bf16_f32 v163, v142, v143
	s_add_i32 s33, s54, 2
	s_cmp_ge_i32 s33, s89
	s_cselect_b64 s[52:53], -1, 0
	s_and_b64 vcc, exec, s[52:53]
	s_cbranch_vccnz .LBB0_941
	s_add_i32 s4, s92, s86
	v_lshl_add_u64 v[130:131], v[236:237], 0, s[22:23]
	s_mov_b32 m0, s4
	s_nop 0
	global_load_lds_dwordx4 v[130:131], off
.LBB0_941:
	s_add_i32 s4, s92, 0x2000
	s_cmpk_lg_i32 s92, 0x4000
	s_cselect_b32 s90, s4, 0
	s_cmp_lt_i32 s54, s89
	s_cselect_b64 s[56:57], -1, 0
	s_cmp_ge_i32 s54, s89
	s_cbranch_scc1 .LBB0_943
	s_lshl_b32 s4, s90, 1
	v_lshl_add_u64 v[130:131], v[234:235], 0, s[24:25]
	s_add_i32 s4, s4, s87
	s_mov_b32 m0, s4
	s_nop 0
	global_load_lds_dwordx4 v[130:131], off
	v_lshl_add_u64 v[132:133], v[234:235], 0, s[26:27]
	s_addk_i32 s4, 0x2000
	s_mov_b32 m0, s4
	s_nop 0
	global_load_lds_dwordx4 v[132:133], off

.LBB0_1179:
	s_add_u32 s2, s12, 0x54000000
	s_addc_u32 s3, s13, 0
	s_add_u32 s20, s14, 0xd100000
	s_addc_u32 s21, s15, 0
	s_abs_i32 s19, s18
	v_cvt_f32_u32_e32 v0, s19
	s_add_i32 s22, s18, 0x7fff
	s_sub_i32 s23, 0xffff8001, s18
	s_xor_b32 s18, s22, s18
	v_rcp_iflag_f32_e32 v0, v0
	s_max_i32 s22, s22, s23
	s_sub_i32 s23, 0, s19
	s_ashr_i32 s18, s18, 31
	v_mul_f32_e32 v0, 0x4f7ffffe, v0
	v_cvt_u32_f32_e32 v0, v0
	s_nop 0
	v_readfirstlane_b32 s24, v0
	s_mul_i32 s23, s23, s24
	s_mul_hi_u32 s23, s24, s23
	s_add_i32 s24, s24, s23
	s_mul_hi_u32 s23, s22, s24
	s_mul_i32 s24, s23, s19
	s_sub_i32 s22, s22, s24
	s_add_i32 s25, s23, 1
	s_sub_i32 s24, s22, s19
	s_cmp_ge_u32 s22, s19
	s_cselect_b32 s23, s25, s23
	s_cselect_b32 s22, s24, s22
	s_add_i32 s24, s23, 1
	s_cmp_ge_u32 s22, s19
	s_cselect_b32 s19, s24, s23
	s_xor_b32 s19, s19, s18
	s_sub_i32 s19, s19, s18
	s_mul_i32 s18, s19, s34
	s_add_i32 s19, s18, s19
	s_min_i32 s26, s19, 0x8000
	s_mul_i32 s98, s34, 18
	s_add_i32 s99, s34, 0xfffffa00
	s_mul_i32 s99, s99, 10
	s_addk_i32 s99, 0x6c00
	s_cmpk_lt_i32 s34, 0x600
	s_cselect_b32 s18, s98, s99
	s_cselect_b32 s98, 18, 10
	s_add_i32 s26, s18, s98
	s_cmp_lt_i32 s18, s26
	s_cselect_b64 s[22:23], -1, 0
	s_cmp_ge_i32 s18, s26
	s_cbranch_scc1 .LBB0_1181
	s_ashr_i32 s19, s18, 31
	s_lshl_b64 s[24:25], s[18:19], 11
	s_add_u32 s34, s20, s24
	s_addc_u32 s35, s21, s25
	s_add_u32 s24, s2, s24
	s_addc_u32 s25, s3, s25
	global_load_dwordx4 v[84:87], v96, s[24:25]
	global_load_dwordx4 v[80:83], v96, s[24:25] offset:1024
	global_load_dwordx4 v[92:95], v96, s[34:35]
	global_load_dwordx4 v[88:91], v96, s[34:35] offset:1024

.LBB0_1790:
	v_cmp_le_u32_e32 vcc, s24, v149
	s_xor_b64 s[18:19], s[20:21], -1
	s_and_b64 s[22:23], s[18:19], vcc
	s_waitcnt vmcnt(0) expcnt(0) lgkmcnt(0)
	s_barrier
	s_and_saveexec_b64 s[18:19], s[22:23]
	ds_write_b128 v228, v[4:7]
	s_or_b64 exec, exec, s[18:19]
	s_add_i32 s25, s24, -1
	v_min_i32_e32 v2, s25, v143
	s_mul_i32 s44, s58, 0x8200
	v_ashrrev_i32_e32 v3, 31, v2
	v_lshl_add_u64 v[2:3], s[44:45], 0, v[2:3]
	v_lshlrev_b64 v[156:157], 9, v[2:3]
	v_min_i32_e32 v2, s25, v206
	v_ashrrev_i32_e32 v3, 31, v2
	v_lshl_add_u64 v[2:3], s[44:45], 0, v[2:3]
	s_lshl_b32 s18, s58, 4
	v_lshlrev_b64 v[158:159], 9, v[2:3]
	v_min_i32_e32 v2, s25, v207
	s_or_b32 s18, s18, s57
	v_ashrrev_i32_e32 v3, 31, v2
	s_mul_i32 s18, s18, 0x8200
	s_cmp_lt_i32 s74, s24
	v_lshl_add_u64 v[2:3], s[44:45], 0, v[2:3]
	v_or_b32_e32 v1, s18, v145
	s_cselect_b64 s[18:19], -1, 0
	s_ashr_i32 s63, s62, 31
	v_lshlrev_b64 v[160:161], 9, v[2:3]
	v_min_i32_e32 v2, s25, v208
	s_and_b64 s[22:23], s[46:47], s[18:19]
	s_lshl_b64 s[18:19], s[62:63], 10
	v_ashrrev_i32_e32 v3, 31, v2
	s_add_u32 s18, s72, s18
	v_or_b32_e32 v156, v156, v142
	v_lshl_add_u64 v[2:3], s[44:45], 0, v[2:3]
	s_addc_u32 s19, s73, s19
	v_lshlrev_b64 v[162:163], 9, v[2:3]
	v_lshl_add_u64 v[2:3], v[156:157], 1, s[18:19]
	v_or_b32_e32 v158, v158, v144
	v_lshl_add_u64 v[8:9], v[2:3], 0, s[52:53]
	s_mov_b32 m0, s80
	s_nop 0
	global_load_lds_dwordx4 v[8:9], off
	v_lshl_add_u64 v[8:9], v[158:159], 1, s[18:19]
	v_or_b32_e32 v160, v160, v146
	v_lshl_add_u64 v[10:11], v[8:9], 0, s[52:53]
	s_mov_b32 m0, s82
	s_nop 0
	global_load_lds_dwordx4 v[10:11], off
	v_lshl_add_u64 v[10:11], v[160:161], 1, s[18:19]
	v_or_b32_e32 v162, v162, v148
	v_lshl_add_u64 v[12:13], v[10:11], 0, s[52:53]
	s_mov_b32 m0, s83
	s_nop 0
	global_load_lds_dwordx4 v[12:13], off
	v_lshl_add_u64 v[12:13], v[162:163], 1, s[18:19]
	v_lshl_add_u64 v[14:15], v[12:13], 0, s[52:53]
	s_mov_b32 m0, s84
	s_nop 0
	global_load_lds_dwordx4 v[14:15], off
	v_lshl_or_b32 v1, v1, 5, v147
	v_cndmask_b32_e64 v14, 0, 1, s[22:23]
	v_cmp_ne_u32_e64 s[18:19], 1, v14
	s_andn2_b64 vcc, exec, s[22:23]
	v_lshlrev_b32_e32 v14, 1, v1
	s_cbranch_vccnz .LBB0_1794
	s_lshl_b64 s[22:23], s[62:63], 6
	s_add_u32 s22, s42, s22
	s_addc_u32 s23, s43, s23
	v_mov_b32_e32 v15, v0
	v_lshl_add_u64 v[16:17], s[22:23], 0, v[14:15]
	s_mov_b32 m0, s81
	s_nop 0
	global_load_lds_dwordx4 v[16:17], off
.LBB0_1794:
	s_nop 0
	s_mov_b32 m0, s75
	s_nop 0
	global_load_lds_dwordx4 v[2:3], off
	v_mov_b32_e32 v15, v0
	s_mov_b32 m0, s85
	s_nop 0
	global_load_lds_dwordx4 v[8:9], off
	v_cndmask_b32_e64 v1, 0, 1, s[20:21]
	s_mov_b32 m0, s86
	s_nop 0
	global_load_lds_dwordx4 v[10:11], off
	v_lshl_add_u64 v[164:165], s[42:43], 0, v[14:15]
	s_mov_b32 m0, s87
	s_nop 0
	global_load_lds_dwordx4 v[12:13], off
	s_waitcnt vmcnt(0) lgkmcnt(0)
	s_barrier
	v_cmp_ne_u32_e64 s[26:27], 1, v1
	s_andn2_b64 vcc, exec, s[20:21]
	s_cbranch_vccnz .LBB0_1797
	s_add_i32 s20, s62, 64
	s_ashr_i32 s21, s20, 31
	s_lshl_b64 s[22:23], s[20:21], 10
	s_add_u32 s22, s72, s22
	s_addc_u32 s23, s73, s23
	v_lshl_add_u64 v[2:3], v[156:157], 1, s[22:23]
	v_lshl_add_u64 v[2:3], v[2:3], 0, s[52:53]
	s_mov_b32 m0, s88
	s_nop 0
	global_load_lds_dwordx4 v[2:3], off
	v_lshl_add_u64 v[2:3], v[158:159], 1, s[22:23]
	v_lshl_add_u64 v[2:3], v[2:3], 0, s[52:53]
	s_mov_b32 m0, s89
	s_nop 0
	global_load_lds_dwordx4 v[2:3], off
	v_lshl_add_u64 v[2:3], v[160:161], 1, s[22:23]
	v_lshl_add_u64 v[2:3], v[2:3], 0, s[52:53]
	s_mov_b32 m0, s90
	s_nop 0
	global_load_lds_dwordx4 v[2:3], off
	v_lshl_add_u64 v[2:3], v[162:163], 1, s[22:23]
	v_lshl_add_u64 v[2:3], v[2:3], 0, s[52:53]
	s_mov_b32 m0, s91
	s_nop 0
	global_load_lds_dwordx4 v[2:3], off
	s_and_b64 vcc, exec, s[18:19]
	s_cbranch_vccnz .LBB0_1797
	s_lshl_b64 s[20:21], s[20:21], 6
	v_lshl_add_u64 v[2:3], v[164:165], 0, s[20:21]
	s_mov_b32 m0, s92
	s_nop 0
	global_load_lds_dwordx4 v[2:3], off
.LBB0_1797:
	v_add_u32_e32 v247, v196, v210
	v_add_u32_e32 v100, v209, v213
	v_add_u32_e32 v1, v209, v210
	v_add_u32_e32 v248, v196, v211
	v_add_u32_e32 v2, v209, v211
	v_add_u32_e32 v249, v196, v212
	v_add_u32_e32 v3, v209, v212
	v_add_u32_e32 v250, v196, v213
	ds_read_b128 v[32:35], v247
	ds_read_b128 v[24:27], v247 offset:256
	ds_read_b128 v[40:43], v1 offset:32768
	ds_read_b128 v[44:47], v1 offset:33024
	ds_read_b128 v[48:51], v1 offset:40960
	ds_read_b128 v[52:55], v1 offset:41216
	ds_read_b128 v[12:15], v248
	ds_read_b128 v[8:11], v248 offset:256
	ds_read_b128 v[56:59], v2 offset:32768
	ds_read_b128 v[60:63], v2 offset:33024
	ds_read_b128 v[64:67], v2 offset:40960
	ds_read_b128 v[68:71], v2 offset:41216
	ds_read_b128 v[36:39], v249
	ds_read_b128 v[28:31], v249 offset:256
	ds_read_b128 v[72:75], v3 offset:32768
	ds_read_b128 v[76:79], v3 offset:33024
	ds_read_b128 v[80:83], v3 offset:40960
	ds_read_b128 v[84:87], v3 offset:41216
	ds_read_b128 v[20:23], v250
	ds_read_b128 v[16:19], v250 offset:256
	ds_read_b128 v[88:91], v100 offset:32768
	ds_read_b128 v[92:95], v100 offset:33024
	ds_read_b128 v[96:99], v100 offset:40960
	ds_read_b128 v[100:103], v100 offset:41216
	v_cmp_gt_u32_e32 vcc, s24, v202
	s_and_b64 s[20:21], s[2:3], vcc
	v_cmp_gt_u32_e32 vcc, s24, v203
	v_cndmask_b32_e64 v153, 0, 1.0, s[20:21]
	s_and_b64 s[20:21], s[4:5], vcc
	v_cndmask_b32_e64 v155, 0, 1.0, s[20:21]
	v_cmp_gt_u32_e32 vcc, s24, v121
	v_cmp_gt_u32_e64 s[20:21], s24, v138
	s_and_b64 s[22:23], s[6:7], vcc
	s_and_b64 s[20:21], s[8:9], s[20:21]
	v_cmp_gt_u32_e32 vcc, s24, v204
	v_cndmask_b32_e64 v166, 0, 1.0, s[20:21]
	s_and_b64 s[20:21], s[10:11], vcc
	v_cmp_gt_u32_e32 vcc, s24, v205
	v_cndmask_b32_e64 v245, 0, 1.0, s[20:21]
	s_and_b64 s[20:21], s[12:13], vcc
	v_cndmask_b32_e64 v246, 0, 1.0, s[20:21]
	v_cmp_gt_u32_e32 vcc, s24, v139
	v_cmp_gt_u32_e64 s[20:21], s24, v140
	v_cndmask_b32_e64 v167, 0, 1.0, s[22:23]
	s_and_b64 s[22:23], s[14:15], vcc
	s_and_b64 s[20:21], s[16:17], s[20:21]
	v_cndmask_b32_e64 v169, 0, 1.0, s[22:23]
	v_cndmask_b32_e64 v168, 0, 1.0, s[20:21]
	s_waitcnt lgkmcnt(14)
	v_mfma_f32_16x16x32_bf16 v[40:43], v[40:43], v[32:35], 0
	v_cvt_pk_bf16_f32 v2, v170, v171
	v_cvt_pk_bf16_f32 v3, v172, v173
	s_and_b64 vcc, exec, s[26:27]
	v_mfma_f32_16x16x32_bf16 v[48:51], v[48:51], v[32:35], 0
	v_mfma_f32_16x16x32_bf16 v[56:59], v[56:59], v[12:15], 0
	s_waitcnt lgkmcnt(13)
	v_mfma_f32_16x16x32_bf16 v[64:67], v[64:67], v[12:15], 0
	s_waitcnt lgkmcnt(9)
	v_mfma_f32_16x16x32_bf16 v[40:43], v[72:75], v[36:39], v[40:43]
	s_waitcnt lgkmcnt(7)
	v_mfma_f32_16x16x32_bf16 v[48:51], v[80:83], v[36:39], v[48:51]
	s_waitcnt lgkmcnt(3)
	v_mfma_f32_16x16x32_bf16 v[56:59], v[88:91], v[20:23], v[56:59]
	s_waitcnt lgkmcnt(1)
	v_mfma_f32_16x16x32_bf16 v[64:67], v[96:99], v[20:23], v[64:67]
	v_mfma_f32_16x16x32_bf16 v[40:43], v[44:47], v[24:27], v[40:43]
	v_mfma_f32_16x16x32_bf16 v[44:47], v[52:55], v[24:27], v[48:51]
	v_mfma_f32_16x16x32_bf16 v[48:51], v[60:63], v[8:11], v[56:59]
	v_mfma_f32_16x16x32_bf16 v[52:55], v[68:71], v[8:11], v[64:67]
	s_nop 1
	v_cvt_pk_bf16_f32 v56, v174, v175
	v_cvt_pk_bf16_f32 v57, v180, v181
	ds_write2st64_b64 v240, v[2:3], v[56:57] offset1:17
	v_mfma_f32_16x16x32_bf16 v[40:43], v[76:79], v[28:31], v[40:43]
	v_cvt_pk_bf16_f32 v2, v176, v177
	v_cvt_pk_bf16_f32 v3, v182, v183
	v_cvt_pk_bf16_f32 v56, v184, v185
	v_mfma_f32_16x16x32_bf16 v[48:51], v[92:95], v[16:19], v[48:51]
	v_cvt_pk_bf16_f32 v57, v186, v187
	ds_write2st64_b64 v241, v[2:3], v[56:57] offset1:17
	v_mfma_f32_16x16x32_bf16 v[44:47], v[84:87], v[28:31], v[44:47]
	s_nop 4
	v_add_f32_e64 v2, v42, v50
	v_add_f32_e64 v3, v43, v51
	v_pk_add_f32 v[48:49], v[40:41], v[48:49]
	s_waitcnt lgkmcnt(2)
	v_mfma_f32_16x16x32_bf16 v[40:43], v[100:103], v[16:19], v[52:55]
	v_mul_f32_e32 v1, v153, v48
	v_pk_mul_f32 v[2:3], v[166:167], v[2:3]
	s_nop 5
	v_pk_add_f32 v[42:43], v[46:47], v[42:43]
	v_pk_add_f32 v[40:41], v[44:45], v[40:41]
	v_mul_f32_e32 v44, v155, v49
	v_cvt_pk_bf16_f32 v44, v1, v44
	v_cvt_pk_bf16_f32 v45, v2, v3
	v_mul_f32_e32 v1, v245, v40
	v_mul_f32_e32 v2, v246, v41
	v_pk_mul_f32 v[40:41], v[168:169], v[42:43]
	v_cvt_pk_bf16_f32 v2, v1, v2
	v_cvt_pk_bf16_f32 v3, v40, v41
	ds_write2_b64 v242, v[44:45], v[2:3] offset1:4
	s_waitcnt lgkmcnt(0)
	s_barrier
	s_cbranch_vccnz .LBB0_1799
	s_lshl_b64 s[20:21], s[62:63], 10
	s_add_u32 s20, s72, s20
	s_addc_u32 s21, s73, s21
	s_add_u32 s20, s20, 0x10000
	s_addc_u32 s21, s21, 0
	v_lshl_add_u64 v[2:3], v[156:157], 1, s[20:21]
	s_mov_b32 m0, s75
	s_nop 0
	global_load_lds_dwordx4 v[2:3], off
	v_lshl_add_u64 v[2:3], v[158:159], 1, s[20:21]
	s_mov_b32 m0, s85
	s_nop 0
	global_load_lds_dwordx4 v[2:3], off
	v_lshl_add_u64 v[2:3], v[160:161], 1, s[20:21]
	s_mov_b32 m0, s86
	s_nop 0
	global_load_lds_dwordx4 v[2:3], off
	v_lshl_add_u64 v[2:3], v[162:163], 1, s[20:21]
	s_mov_b32 m0, s87
	s_nop 0
	global_load_lds_dwordx4 v[2:3], off

.LBB0_1807:
	s_or_b64 exec, exec, s[64:65]
	s_and_b32 s35, s29, 1
	s_lshl_b32 s27, s35, 15
	s_add_i32 s34, s27, 0
	v_add_u32_e32 v1, s34, v197
	v_add_u32_e32 v16, v1, v212
	v_add_u32_e32 v2, v1, v210
	v_add_u32_e32 v3, v1, v211
	v_add_u32_e32 v1, v1, v213
	ds_read_b128 v[24:27], v247
	ds_read_b128 v[28:31], v247 offset:256
	ds_read_b128 v[40:43], v2 offset:32768
	ds_read_b128 v[44:47], v2 offset:33024
	ds_read_b128 v[48:51], v2 offset:40960
	ds_read_b128 v[52:55], v2 offset:41216
	ds_read_b128 v[12:15], v248
	ds_read_b128 v[8:11], v248 offset:256
	ds_read_b128 v[56:59], v3 offset:32768
	ds_read_b128 v[60:63], v3 offset:33024
	ds_read_b128 v[64:67], v3 offset:40960
	ds_read_b128 v[68:71], v3 offset:41216
	ds_read_b128 v[36:39], v249
	ds_read_b128 v[32:35], v249 offset:256
	ds_read_b128 v[72:75], v16 offset:32768
	ds_read_b128 v[76:79], v16 offset:33024
	ds_read_b128 v[80:83], v16 offset:40960
	ds_read_b128 v[84:87], v16 offset:41216
	ds_read_b128 v[20:23], v250
	ds_read_b128 v[16:19], v250 offset:256
	ds_read_b128 v[88:91], v1 offset:32768
	ds_read_b128 v[92:95], v1 offset:33024
	ds_read_b128 v[96:99], v1 offset:40960
	ds_read_b128 v[100:103], v1 offset:41216
	s_add_i32 s33, s29, 1
	s_cmp_lt_u32 s33, s95
	s_cselect_b64 s[64:65], -1, 0
	s_cmp_ge_u32 s33, s95
	s_cbranch_scc1 .LBB0_1811
	s_ashr_i32 s27, s26, 31
	s_lshl_b64 s[34:35], s[26:27], 10
	s_add_u32 s76, s72, s34
	s_addc_u32 s77, s73, s35
	s_and_b32 s34, s33, 1
	s_lshl_b32 s35, s34, 15
	v_lshl_add_u64 v[2:3], v[156:157], 1, s[76:77]
	s_add_i32 s35, s75, s35
	v_lshl_add_u64 v[2:3], v[2:3], 0, s[52:53]
	s_add_i32 s44, s35, 0x8000
	s_mov_b32 m0, s44
	s_nop 0
	global_load_lds_dwordx4 v[2:3], off
	v_lshl_add_u64 v[2:3], v[158:159], 1, s[76:77]
	v_lshl_add_u64 v[2:3], v[2:3], 0, s[52:53]
	s_add_i32 s44, s35, 0x8400
	s_mov_b32 m0, s44
	s_nop 0
	global_load_lds_dwordx4 v[2:3], off
	v_lshl_add_u64 v[2:3], v[160:161], 1, s[76:77]
	v_lshl_add_u64 v[2:3], v[2:3], 0, s[52:53]
	s_add_i32 s44, s35, 0x8800
	s_mov_b32 m0, s44
	s_nop 0
	global_load_lds_dwordx4 v[2:3], off
	v_lshl_add_u64 v[2:3], v[162:163], 1, s[76:77]
	v_lshl_add_u64 v[2:3], v[2:3], 0, s[52:53]
	s_add_i32 s35, s35, 0x8c00
	s_mov_b32 m0, s35
	s_nop 0
	global_load_lds_dwordx4 v[2:3], off
	s_and_b64 vcc, exec, s[18:19]
	s_cbranch_vccnz .LBB0_1810
	s_lshl_b64 s[76:77], s[26:27], 6
	s_lshl_b32 s27, s34, 12
	v_lshl_add_u64 v[2:3], v[164:165], 0, s[76:77]
	s_add_i32 s27, s81, s27
	s_mov_b32 m0, s27
	s_nop 0
	global_load_lds_dwordx4 v[2:3], off

.LBB0_1811:
	s_and_b32 s35, s29, 1
	s_lshl_b32 s27, s35, 15
	s_add_i32 s34, s27, 0
	s_waitcnt lgkmcnt(14)
	v_mfma_f32_16x16x32_bf16 v[40:43], v[40:43], v[24:27], 0
	v_cvt_pk_bf16_f32 v2, v188, v189
	v_cvt_pk_bf16_f32 v3, v186, v187
	s_andn2_b64 vcc, exec, s[64:65]
	v_mfma_f32_16x16x32_bf16 v[48:51], v[48:51], v[24:27], 0
	v_mfma_f32_16x16x32_bf16 v[56:59], v[56:59], v[12:15], 0
	s_waitcnt lgkmcnt(13)
	v_mfma_f32_16x16x32_bf16 v[64:67], v[64:67], v[12:15], 0
	s_waitcnt lgkmcnt(9)
	v_mfma_f32_16x16x32_bf16 v[40:43], v[72:75], v[36:39], v[40:43]
	s_waitcnt lgkmcnt(7)
	v_mfma_f32_16x16x32_bf16 v[48:51], v[80:83], v[36:39], v[48:51]
	s_waitcnt lgkmcnt(3)
	v_mfma_f32_16x16x32_bf16 v[56:59], v[88:91], v[20:23], v[56:59]
	s_waitcnt lgkmcnt(1)
	v_mfma_f32_16x16x32_bf16 v[64:67], v[96:99], v[20:23], v[64:67]
	v_mfma_f32_16x16x32_bf16 v[40:43], v[44:47], v[28:31], v[40:43]
	v_mfma_f32_16x16x32_bf16 v[44:47], v[52:55], v[28:31], v[48:51]
	v_mfma_f32_16x16x32_bf16 v[48:51], v[60:63], v[8:11], v[56:59]
	v_mfma_f32_16x16x32_bf16 v[52:55], v[68:71], v[8:11], v[64:67]
	s_nop 1
	v_cvt_pk_bf16_f32 v56, v184, v185
	v_cvt_pk_bf16_f32 v57, v182, v183
	ds_write2st64_b64 v240, v[2:3], v[56:57] offset1:17
	v_mfma_f32_16x16x32_bf16 v[40:43], v[76:79], v[32:35], v[40:43]
	v_cvt_pk_bf16_f32 v2, v176, v177
	v_cvt_pk_bf16_f32 v3, v174, v175
	v_cvt_pk_bf16_f32 v56, v172, v173
	v_mfma_f32_16x16x32_bf16 v[48:51], v[92:95], v[16:19], v[48:51]
	v_cvt_pk_bf16_f32 v57, v170, v171
	ds_write2st64_b64 v241, v[2:3], v[56:57] offset1:17
	v_mfma_f32_16x16x32_bf16 v[44:47], v[84:87], v[32:35], v[44:47]
	s_nop 4
	v_add_f32_e64 v2, v42, v50
	v_add_f32_e64 v3, v43, v51
	v_pk_add_f32 v[48:49], v[40:41], v[48:49]
	s_waitcnt lgkmcnt(2)
	v_mfma_f32_16x16x32_bf16 v[40:43], v[100:103], v[16:19], v[52:55]
	v_mul_f32_e32 v1, v153, v48
	v_pk_mul_f32 v[2:3], v[166:167], v[2:3]
	s_nop 5
	v_pk_add_f32 v[42:43], v[46:47], v[42:43]
	v_pk_add_f32 v[40:41], v[44:45], v[40:41]
	v_mul_f32_e32 v44, v155, v49
	v_cvt_pk_bf16_f32 v44, v1, v44
	v_cvt_pk_bf16_f32 v45, v2, v3
	v_mul_f32_e32 v1, v245, v40
	v_mul_f32_e32 v2, v246, v41
	v_pk_mul_f32 v[40:41], v[168:169], v[42:43]
	v_cvt_pk_bf16_f32 v2, v1, v2
	v_cvt_pk_bf16_f32 v3, v40, v41
	ds_write2_b64 v242, v[44:45], v[2:3] offset1:4
	s_waitcnt lgkmcnt(0)
	s_barrier
	s_lshl_b32 s27, s35, 12
	s_add_i32 s27, s27, 0
	s_add_i32 s27, s27, 0x18000
	v_add3_u32 v1, s27, v200, v214
	v_add_u32_e32 v2, s34, v218
	v_add_u32_e32 v56, s34, v220
	ds_read_b128 v[84:87], v243
	ds_read_b128 v[52:55], v243 offset:64
	ds_read_b128 v[88:91], v243 offset:128
	ds_read_b128 v[48:51], v243 offset:192
	ds_read_b128 v[92:95], v243 offset:256
	ds_read_b128 v[44:47], v243 offset:320
	ds_read_b128 v[96:99], v243 offset:384
	ds_read_b128 v[40:43], v243 offset:448
	ds_read_b128 v[60:63], v251
	ds_read_b128 v[108:111], v251 offset:64
	ds_read_b64_tr_b16 v[116:117], v1
	ds_read_b64_tr_b16 v[118:119], v1 offset:256
	ds_read_b64_tr_b16 v[112:113], v1 offset:2048
	ds_read_b64_tr_b16 v[114:115], v1 offset:2304
	v_add_u32_e32 v1, s27, v216
	v_add3_u32 v3, v2, v215, v201
	v_add3_u32 v56, v56, v219, v201
	v_add_u32_e32 v58, v1, v214
	ds_read_b64_tr_b16 v[80:81], v3 offset:32768
	ds_read_b64_tr_b16 v[82:83], v56 offset:32768
	ds_read_b64_tr_b16 v[64:65], v58
	ds_read_b64_tr_b16 v[56:57], v58 offset:32
	v_add_u32_e32 v3, s34, v223
	v_add3_u32 v3, v3, v222, v201
	v_add_u32_e32 v68, s34, v225
	v_add_u32_e32 v59, s34, v226
	v_add3_u32 v2, v2, v221, v201
	v_add3_u32 v69, v68, v215, v201
	v_add3_u32 v70, v59, v219, v201
	ds_read_b64_tr_b16 v[66:67], v58 offset:256
	ds_read_b64_tr_b16 v[104:105], v2 offset:32768
	ds_read_b64_tr_b16 v[106:107], v3 offset:32768
	ds_read_b64_tr_b16 v[58:59], v58 offset:288
	v_add_u32_e32 v3, s34, v227
	v_add_u32_e32 v1, v1, v224
	v_add3_u32 v2, v68, v221, v201
	v_add3_u32 v3, v3, v222, v201
	ds_read_b64_tr_b16 v[68:69], v69 offset:32768
	ds_read_b64_tr_b16 v[70:71], v70 offset:32768
	ds_read_b64_tr_b16 v[72:73], v2 offset:32768
	ds_read_b64_tr_b16 v[74:75], v3 offset:32768
	ds_read_b64_tr_b16 v[100:101], v1
	ds_read_b64_tr_b16 v[76:77], v1 offset:32
	ds_read_b64_tr_b16 v[102:103], v1 offset:256
	ds_read_b64_tr_b16 v[78:79], v1 offset:288
	s_cbranch_vccnz .LBB0_1813
	s_ashr_i32 s27, s26, 31
	s_lshl_b64 s[64:65], s[26:27], 10
	s_add_u32 s64, s72, s64
	s_addc_u32 s65, s73, s65
	v_lshl_add_u64 v[2:3], v[156:157], 1, s[64:65]
	s_mov_b32 m0, s75
	s_nop 0
	global_load_lds_dwordx4 v[2:3], off
	v_lshl_add_u64 v[2:3], v[158:159], 1, s[64:65]
	s_mov_b32 m0, s85
	s_nop 0
	global_load_lds_dwordx4 v[2:3], off
	v_lshl_add_u64 v[2:3], v[160:161], 1, s[64:65]
	s_mov_b32 m0, s86
	s_nop 0
	global_load_lds_dwordx4 v[2:3], off
	v_lshl_add_u64 v[2:3], v[162:163], 1, s[64:65]
	s_mov_b32 m0, s87
	s_nop 0
	global_load_lds_dwordx4 v[2:3], off
.LBB0_1813:
	s_and_b64 vcc, exec, s[20:21]
	s_cbranch_vccnz .LBB0_1815
	s_waitcnt lgkmcnt(14)
	v_mfma_f32_16x16x32_bf16 v[60:63], v[116:119], v[60:63], 0
	s_and_b64 vcc, exec, s[22:23]
	s_cbranch_vccz .LBB0_1816
	s_branch .LBB0_1817

.LBB0_2442:
	s_or_b64 exec, exec, s[26:27]
	s_add_i32 s29, s73, -1
	s_mul_i32 s26, s72, 0x8200
	s_add_u32 s26, s26, s78
	v_min_i32_e32 v0, s29, v37
	s_addc_u32 s27, 0, s25
	v_ashrrev_i32_e32 v1, 31, v0
	v_lshl_add_u64 v[0:1], s[26:27], 0, v[0:1]
	v_min_i32_e32 v2, s29, v89
	v_lshlrev_b64 v[0:1], 7, v[0:1]
	v_ashrrev_i32_e32 v3, 31, v2
	v_or_b32_e32 v0, v0, v56
	v_lshl_add_u64 v[2:3], s[26:27], 0, v[2:3]
	v_lshlrev_b64 v[2:3], 7, v[2:3]
	v_lshlrev_b64 v[66:67], 1, v[0:1]
	v_or_b32_e32 v2, v2, v58
	v_lshl_add_u64 v[8:9], s[20:21], 0, v[34:35]
	v_lshl_add_u64 v[0:1], s[40:41], 0, v[66:67]
	s_mov_b32 m0, s89
	s_nop 0
	global_load_lds_dwordx4 v[0:1], off
	v_lshl_add_u64 v[0:1], s[42:43], 0, v[66:67]
	s_mov_b32 m0, s90
	s_nop 0
	global_load_lds_dwordx4 v[0:1], off
	v_lshlrev_b64 v[68:69], 1, v[2:3]
	v_lshl_add_u64 v[0:1], s[40:41], 0, v[68:69]
	s_mov_b32 m0, s91
	s_nop 0
	global_load_lds_dwordx4 v[0:1], off
	v_lshlrev_b64 v[8:9], 4, v[8:9]
	v_lshl_add_u64 v[0:1], s[42:43], 0, v[68:69]
	s_mov_b32 m0, s92
	s_nop 0
	global_load_lds_dwordx4 v[0:1], off
	s_and_b64 s[26:27], s[48:49], s[22:23]
	v_or_b32_e32 v8, v8, v36
	v_cndmask_b32_e64 v0, 0, 1, s[26:27]
	v_cmp_ne_u32_e64 s[20:21], 1, v0
	s_andn2_b64 vcc, exec, s[26:27]
	v_lshl_add_u64 v[76:77], v[8:9], 1, s[46:47]
	s_cbranch_vccnz .LBB0_2444
	s_mov_b32 m0, s88
	s_nop 0
	global_load_lds_dwordx4 v[76:77], off
.LBB0_2444:
	s_ashr_i32 s25, s24, 31
	s_lshl_b64 s[74:75], s[24:25], 12
	s_add_u32 s26, s82, s74
	s_addc_u32 s27, s83, s75
	s_lshl_b32 s50, s72, 7
	s_lshl_b64 s[24:25], s[50:51], 2
	s_add_u32 s24, s26, s24
	s_addc_u32 s25, s27, s25
	s_add_u32 s26, s24, s60
	s_addc_u32 s27, s25, s61
	global_load_dwordx4 v[8:11], v64, s[26:27]
	s_waitcnt vmcnt(0) lgkmcnt(0)
	s_barrier
	v_cndmask_b32_e64 v0, 0, 1, s[22:23]
	v_cmp_ne_u32_e64 s[24:25], 1, v0
	s_andn2_b64 vcc, exec, s[22:23]
	s_waitcnt vmcnt(0)
	v_mov_b64_e32 v[0:1], v[8:9]
	v_mov_b64_e32 v[2:3], v[10:11]
	s_cbranch_vccnz .LBB0_2448
	v_lshl_add_u64 v[0:1], s[56:57], 0, v[66:67]
	s_mov_b32 m0, s93
	s_nop 0
	global_load_lds_dwordx4 v[0:1], off
	v_lshl_add_u64 v[0:1], s[58:59], 0, v[66:67]
	s_mov_b32 m0, s94
	s_nop 0
	global_load_lds_dwordx4 v[0:1], off
	v_lshl_add_u64 v[0:1], s[56:57], 0, v[68:69]
	s_mov_b32 m0, s95
	s_nop 0
	global_load_lds_dwordx4 v[0:1], off
	v_lshl_add_u64 v[0:1], s[58:59], 0, v[68:69]
	s_mov_b32 m0, s96
	s_nop 0
	global_load_lds_dwordx4 v[0:1], off
	s_and_b64 vcc, exec, s[20:21]
	s_cbranch_vccnz .LBB0_2447
	v_lshl_add_u64 v[0:1], v[76:77], 0, s[66:67]
	s_mov_b32 m0, s97
	s_nop 0
	global_load_lds_dwordx4 v[0:1], off

.LBB0_2457:
	s_or_b64 exec, exec, s[74:75]
	s_add_i32 s76, s29, 1
	v_mov_b64_e32 v[10:11], v[2:3]
	v_mov_b64_e32 v[8:9], v[0:1]
	s_and_b32 s28, s29, 1
	s_lshl_b32 s29, s28, 14
	s_add_i32 s29, s29, 0
	v_add_u32_e32 v134, s29, v55
	v_add_u32_e32 v142, s29, v57
	v_add_u32_e32 v12, v134, v92
	v_add_u32_e32 v20, v142, v92
	v_add_u32_e32 v24, v134, v93
	v_add_u32_e32 v122, v142, v93
	v_add_u32_e32 v126, v134, v94
	v_add_u32_e32 v135, v142, v94
	v_add_u32_e32 v138, v134, v95
	v_add_u32_e32 v146, v142, v95
	ds_read_b128 v[12:15], v12
	ds_read_b128 v[16:19], v20 offset:32768
	ds_read_b128 v[20:23], v20 offset:36864
	ds_read_b128 v[24:27], v24
	ds_read_b128 v[118:121], v122 offset:32768
	ds_read_b128 v[122:125], v122 offset:36864
	ds_read_b128 v[126:129], v126
	ds_read_b128 v[130:133], v135 offset:32768
	ds_read_b128 v[134:137], v135 offset:36864
	ds_read_b128 v[138:141], v138
	ds_read_b128 v[142:145], v146 offset:32768
	ds_read_b128 v[146:149], v146 offset:36864
	s_cmp_ge_u32 s76, s77
	s_cbranch_scc1 .LBB0_2461
	s_and_b32 s74, s76, 1
	s_lshl_b32 s75, s74, 14
	v_lshl_add_u64 v[8:9], s[72:73], 0, v[66:67]
	s_add_i32 s75, s89, s75
	s_mov_b32 vcc_lo, m0
	s_mov_b32 m0, s75
	s_nop 0
	global_load_lds_dwordx4 v[8:9], off
	s_mov_b32 m0, vcc_lo
	s_add_i32 vcc_lo, s75, 0x8000
	v_lshl_add_u64 v[8:9], s[26:27], 0, v[66:67]
	s_mov_b32 vcc_hi, m0
	s_mov_b32 m0, vcc_lo
	s_nop 0
	global_load_lds_dwordx4 v[8:9], off
	s_mov_b32 m0, vcc_hi
	s_add_i32 vcc_lo, s75, 0x400
	v_lshl_add_u64 v[8:9], s[72:73], 0, v[68:69]
	s_mov_b32 vcc_hi, m0
	s_mov_b32 m0, vcc_lo
	s_nop 0
	global_load_lds_dwordx4 v[8:9], off
	s_mov_b32 m0, vcc_hi
	v_lshl_add_u64 v[8:9], s[26:27], 0, v[68:69]
	s_add_i32 s75, s75, 0x8400
	s_mov_b32 m0, s75
	s_nop 0
	global_load_lds_dwordx4 v[8:9], off
	s_and_b64 vcc, exec, s[20:21]
	s_cbranch_vccnz .LBB0_2460
	s_lshl_b32 s28, s74, 11
	s_add_i32 s28, s88, s28
	s_mov_b32 m0, s28
	s_nop 0
	global_load_lds_dwordx4 v[76:77], off

.LBB0_2461:
	s_add_i32 s28, s76, -1
	s_and_b32 s28, s28, 1
	s_waitcnt lgkmcnt(10)
	v_mfma_f32_16x16x32_bf16 v[16:19], v[16:19], v[12:15], 0
	s_and_b64 vcc, exec, s[22:23]
	s_waitcnt lgkmcnt(9)
	v_mfma_f32_16x16x32_bf16 v[12:15], v[20:23], v[12:15], 0
	s_waitcnt lgkmcnt(7)
	v_mfma_f32_16x16x32_bf16 v[20:23], v[118:121], v[24:27], 0
	v_cvt_pk_bf16_f32 v118, v4, v5
	v_cvt_pk_bf16_f32 v119, v6, v7
	ds_write_b64 v110, v[118:119]
	s_waitcnt lgkmcnt(7)
	v_mfma_f32_16x16x32_bf16 v[24:27], v[122:125], v[24:27], 0
	s_waitcnt lgkmcnt(5)
	v_mfma_f32_16x16x32_bf16 v[16:19], v[130:133], v[126:129], v[16:19]
	s_waitcnt lgkmcnt(2)
	v_mfma_f32_16x16x32_bf16 v[20:23], v[142:145], v[138:141], v[20:23]
	v_mfma_f32_16x16x32_bf16 v[12:15], v[134:137], v[126:129], v[12:15]
	s_nop 6
	v_add_f32_e64 v22, v18, v22
	v_add_f32_e64 v23, v19, v23
	v_pk_add_f32 v[20:21], v[16:17], v[20:21]
	s_waitcnt lgkmcnt(1)
	v_mfma_f32_16x16x32_bf16 v[16:19], v[146:149], v[138:141], v[24:27]
	s_nop 7
	v_pk_add_f32 v[14:15], v[14:15], v[18:19]
	v_pk_add_f32 v[12:13], v[12:13], v[16:17]
	v_mul_f32_e32 v16, v65, v20
	v_mul_f32_e32 v17, v112, v21
	v_pk_mul_f32 v[18:19], v[70:71], v[22:23]
	v_mul_f32_e32 v12, v113, v12
	v_mul_f32_e32 v13, v114, v13
	v_pk_mul_f32 v[14:15], v[72:73], v[14:15]
	v_cvt_pk_bf16_f32 v16, v16, v17
	v_cvt_pk_bf16_f32 v17, v18, v19
	v_cvt_pk_bf16_f32 v12, v12, v13
	v_cvt_pk_bf16_f32 v13, v14, v15
	ds_write_b64 v115, v[16:17]
	ds_write_b64 v116, v[12:13]
	v_lshl_add_u32 v20, s28, 11, v83
	v_add_u32_e32 v21, s29, v97
	v_add_u32_e32 v13, s29, v99
	v_add_u32_e32 v22, s29, v103
	s_waitcnt lgkmcnt(0)
	s_barrier
	v_add3_u32 v12, v21, v96, v36
	v_add3_u32 v14, v13, v98, v36
	v_add_u32_e32 v18, v20, v100
	v_add3_u32 v21, v21, v101, v36
	v_add3_u32 v22, v22, v102, v36
	v_add_u32_e32 v26, v20, v104
	ds_read_b64_tr_b16 v[12:13], v12 offset:32768
	ds_read_b64_tr_b16 v[14:15], v14 offset:32768
	ds_read_b64_tr_b16 v[16:17], v18
	ds_read_b64_tr_b16 v[18:19], v18 offset:128
	ds_read_b64_tr_b16 v[20:21], v21 offset:32768
	ds_read_b64_tr_b16 v[22:23], v22 offset:32768
	ds_read_b64_tr_b16 v[24:25], v26
	ds_read_b64_tr_b16 v[26:27], v26 offset:128
	s_cbranch_vccnz .LBB0_2463
	s_cbranch_execz .LBB0_2464
	s_branch .LBB0_2465

.LBB0_2880:
	s_add_u32 s0, s4, 0x54000000
	s_addc_u32 s1, s5, 0
	s_add_u32 s14, s6, 0xd100000
	s_addc_u32 s15, s7, 0
	s_abs_i32 s13, s12
	v_cvt_f32_u32_e32 v0, s13
	s_add_i32 s16, s12, 0x7fff
	s_sub_i32 s17, 0xffff8001, s12
	s_xor_b32 s12, s16, s12
	v_rcp_iflag_f32_e32 v0, v0
	s_max_i32 s16, s16, s17
	s_sub_i32 s17, 0, s13
	s_ashr_i32 s12, s12, 31
	v_mul_f32_e32 v0, 0x4f7ffffe, v0
	v_cvt_u32_f32_e32 v0, v0
	s_nop 0
	v_readfirstlane_b32 s18, v0
	s_mul_i32 s17, s17, s18
	s_mul_hi_u32 s17, s18, s17
	s_add_i32 s18, s18, s17
	s_mul_hi_u32 s17, s16, s18
	s_mul_i32 s18, s17, s13
	s_sub_i32 s16, s16, s18
	s_add_i32 s19, s17, 1
	s_sub_i32 s18, s16, s13
	s_cmp_ge_u32 s16, s13
	s_cselect_b32 s17, s19, s17
	s_cselect_b32 s16, s18, s16
	s_add_i32 s18, s17, 1
	s_cmp_ge_u32 s16, s13
	s_cselect_b32 s13, s18, s17
	s_xor_b32 s13, s13, s12
	s_sub_i32 s13, s13, s12
	s_mul_i32 s12, s13, s33
	s_add_i32 s13, s12, s13
	s_min_i32 s20, s13, 0x8000
	s_mul_i32 s98, s33, 18
	s_add_i32 s99, s33, 0xfffffa00
	s_mul_i32 s99, s99, 10
	s_addk_i32 s99, 0x6c00
	s_cmpk_lt_i32 s33, 0x600
	s_cselect_b32 s12, s98, s99
	s_cselect_b32 s98, 18, 10
	s_add_i32 s20, s12, s98
	s_cmp_lt_i32 s12, s20
	s_cselect_b64 s[16:17], -1, 0
	s_cmp_ge_i32 s12, s20
	s_cbranch_scc1 .LBB0_2882
	s_ashr_i32 s13, s12, 31
	s_lshl_b64 s[18:19], s[12:13], 11
	s_add_u32 s22, s14, s18
	s_addc_u32 s23, s15, s19
	s_add_u32 s18, s0, s18
	s_addc_u32 s19, s1, s19
	global_load_dwordx4 v[52:55], v64, s[18:19]
	global_load_dwordx4 v[48:51], v64, s[18:19] offset:1024
	global_load_dwordx4 v[60:63], v64, s[22:23]
	global_load_dwordx4 v[56:59], v64, s[22:23] offset:1024
